# NSA compressed passes 1 and 2: tiles fully valid for every lane take a QK block without per-element limit compares
# baseline (speedup 1.0000x reference)
; #define EXP2F(x) __builtin_amdgcn_exp2f(x)
; #define SB0 __builtin_amdgcn_sched_barrier(0)
; __device__ __forceinline__ void qk64_lim(const bf16x8 (&kq)[8], const bf16x8 (&qf)[2], float scale, int lim2,
;                                          f32x4 (&st)[4]) {
; #pragma unroll
;   for (int kt = 0; kt < 4; ++kt) {
;     f32x4 z = {0.f, 0.f, 0.f, 0.f};
;     z = mfma16(kq[2 * kt], qf[0], z);
;     z = mfma16(kq[2 * kt + 1], qf[1], z);
; #pragma unroll
;     for (int r = 0; r < 4; ++r) st[kt][r] = ((kt * 16 + r) <= lim2) ? z[r] * scale : -INFINITY;
;   }
; }
; __device__ __forceinline__ void phase_nsa_attn(const Params& p, char* smem, volatile LAS unsigned* vb_) {
;     ...
;         for (int i = 0; i < ntile; ++i) {
;           const int n0 = i * 64;
;           const int nn = (i + 1 < ntile ? i + 1 : i) * 64;
;           f32x4 st[4];
;           qk64_lim(kA, qf, scale, nvalid - 1 - n0 - q * 4, st);
;           SB0;
;           k_load64(kA, Kb + (size_t)nn * 64, lane);
;           SB0;
; #pragma unroll
;           for (int kt = 0; kt < 4; ++kt)
; #pragma unroll
;             for (int r = 0; r < 4; ++r) st[kt][r] = EXP2F(st[kt][r] - m) * invl;
;           pv64(vA, st, o);
.Lc2_fast:
	s_waitcnt vmcnt(15)
	v_mfma_f32_16x16x32_bf16 v[68:71], v[68:71], v[4:7], 0
	s_waitcnt vmcnt(5)
	v_mov_b64_e32 v[102:103], v[82:83]
	s_mov_b32 s20, s11
	s_add_i32 s11, s11, 1
	v_mfma_f32_16x16x32_bf16 v[64:67], v[64:67], v[8:11], v[68:71]
	v_mov_b64_e32 v[100:101], v[80:81]
	v_mov_b32_e32 v0, s20
	v_mov_b32_e32 v80, s11
	v_mfma_f32_16x16x32_bf16 v[60:63], v[60:63], v[4:7], 0
	v_cmp_lt_i32_e32 vcc, s11, v159
	s_waitcnt vmcnt(4)
	v_mov_b64_e32 v[94:95], v[86:87]
	s_nop 0
	v_cndmask_b32_e32 v0, v0, v80, vcc
	v_mfma_f32_16x16x32_bf16 v[52:55], v[52:55], v[8:11], v[60:63]
	v_mov_b64_e32 v[92:93], v[84:85]
	v_mul_f32_e32 v82, 0x3e38aa3b, v64
	v_mfma_f32_16x16x32_bf16 v[44:47], v[44:47], v[4:7], 0
	s_waitcnt vmcnt(1)
	v_mov_b64_e32 v[98:99], v[90:91]
	v_mul_f32_e32 v83, 0x3e38aa3b, v65
	v_mfma_f32_16x16x32_bf16 v[40:43], v[40:43], v[8:11], v[44:47]
	v_mov_b64_e32 v[96:97], v[88:89]
	v_mul_f32_e32 v84, 0x3e38aa3b, v66
	v_mfma_f32_16x16x32_bf16 v[36:39], v[36:39], v[4:7], 0
	v_mul_f32_e32 v85, 0x3e38aa3b, v67
	v_mfma_f32_16x16x32_bf16 v[32:35], v[32:35], v[8:11], v[36:39]
	v_lshlrev_b32_e32 v0, 6, v0
	v_mul_f32_e32 v86, 0x3e38aa3b, v52
	v_mul_f32_e32 v87, 0x3e38aa3b, v53
	v_mul_f32_e32 v88, 0x3e38aa3b, v54
	v_mul_f32_e32 v89, 0x3e38aa3b, v55
	v_mul_f32_e32 v90, 0x3e38aa3b, v40
	v_mul_f32_e32 v91, 0x3e38aa3b, v41
	v_mul_f32_e32 v104, 0x3e38aa3b, v42
	v_mul_f32_e32 v105, 0x3e38aa3b, v43
	v_mul_f32_e32 v106, 0x3e38aa3b, v32
	v_mul_f32_e32 v107, 0x3e38aa3b, v33
	v_mul_f32_e32 v108, 0x3e38aa3b, v34
	v_mul_f32_e32 v109, 0x3e38aa3b, v35
	s_branch .Lc2_tail

; #define EXP2F(x) __builtin_amdgcn_exp2f(x)
; #define SB0 __builtin_amdgcn_sched_barrier(0)
; __device__ __forceinline__ void phase_nsa_attn(const Params& p, char* smem, volatile LAS unsigned* vb_) {
;     ...
;         for (int i = 0; i < ntile; ++i) {
;           const int n0 = i * 64;
;           const int nn = (i + 1 < ntile ? i + 1 : i) * 64;
;           f32x4 st[4];
;           qk64_lim(kA, qf, scale, nvalid - 1 - n0 - q * 4, st);
;           SB0;
;           k_load64(kA, Kb + (size_t)nn * 64, lane);
;           SB0;
; #pragma unroll
;           for (int kt = 0; kt < 4; ++kt)
; #pragma unroll
;             for (int r = 0; r < 4; ++r) st[kt][r] = EXP2F(st[kt][r] - m) * invl;
;           pv64(vA, st, o);
;           SB0;
;           v_load64(vA, Vb + (size_t)nn * 64, lane);
;           SB0;
;           float mainv[4], ev[4], eup[4];
; #pragma unroll
;           for (int kt = 0; kt < 4; ++kt) {
;             float acc = 0.f, last = 0.f;
; #pragma unroll
;             for (int r = 0; r < 4; ++r) {
;               float a = st[kt][r];
;               a += __shfl_xor(a, 1);
;               a += __shfl_xor(a, 2);
;               acc += a;
;               last = a;
;             }
;             mainv[kt] = acc; ev[kt] = last;
;           }
; #pragma unroll
;           for (int kt = 0; kt < 4; ++kt) eup[kt] = __shfl(ev[kt], (lane + 48) & 63);
.LBB0_97:
	v_readfirstlane_b32 s98, v179
	s_cmp_gt_i32 s98, 62
	s_cbranch_scc1 .Lc2_fast
	s_waitcnt vmcnt(15)
	v_mfma_f32_16x16x32_bf16 v[68:71], v[68:71], v[4:7], 0
	s_waitcnt vmcnt(5)
	v_mov_b64_e32 v[102:103], v[82:83]
	s_mov_b32 s20, s11
	s_add_i32 s11, s11, 1
	v_mfma_f32_16x16x32_bf16 v[64:67], v[64:67], v[8:11], v[68:71]
	v_mov_b64_e32 v[100:101], v[80:81]
	v_mov_b32_e32 v0, s20
	v_mov_b32_e32 v80, s11
	v_mfma_f32_16x16x32_bf16 v[60:63], v[60:63], v[4:7], 0
	v_cmp_lt_i32_e32 vcc, s11, v159
	s_nop 2
	v_mul_f32_e32 v64, 0x3e38aa3b, v64
	s_waitcnt vmcnt(4)
	v_mov_b64_e32 v[94:95], v[86:87]
	v_cndmask_b32_e32 v0, v0, v80, vcc
	v_cmp_lt_i32_e32 vcc, -1, v179
	v_mfma_f32_16x16x32_bf16 v[52:55], v[52:55], v[8:11], v[60:63]
	v_mov_b64_e32 v[92:93], v[84:85]
	v_cndmask_b32_e32 v82, v203, v64, vcc
	v_mul_f32_e32 v64, 0x3e38aa3b, v65
	v_mfma_f32_16x16x32_bf16 v[44:47], v[44:47], v[4:7], 0
	v_cmp_lt_i32_e32 vcc, 0, v179
	s_nop 2
	v_mul_f32_e32 v52, 0x3e38aa3b, v52
	s_waitcnt vmcnt(1)
	v_mov_b64_e32 v[98:99], v[90:91]
	v_cndmask_b32_e32 v83, v203, v64, vcc
	v_mul_f32_e32 v64, 0x3e38aa3b, v66
	v_cmp_lt_i32_e32 vcc, 1, v179
	v_mfma_f32_16x16x32_bf16 v[40:43], v[40:43], v[8:11], v[44:47]
	v_mov_b64_e32 v[96:97], v[88:89]
	v_cndmask_b32_e32 v84, v203, v64, vcc
	v_mul_f32_e32 v64, 0x3e38aa3b, v67
	v_cmp_lt_i32_e32 vcc, 2, v179
	v_mfma_f32_16x16x32_bf16 v[36:39], v[36:39], v[4:7], 0
	s_nop 2
	v_mul_f32_e32 v40, 0x3e38aa3b, v40
	v_cndmask_b32_e32 v85, v203, v64, vcc
	v_cmp_lt_i32_e32 vcc, 15, v179
	v_mfma_f32_16x16x32_bf16 v[32:35], v[32:35], v[8:11], v[36:39]
	v_lshlrev_b32_e32 v0, 6, v0
	v_cndmask_b32_e32 v86, v203, v52, vcc
	v_mul_f32_e32 v52, 0x3e38aa3b, v53
	v_cmp_lt_i32_e32 vcc, 16, v179
	s_nop 1
	v_cndmask_b32_e32 v87, v203, v52, vcc
	v_mul_f32_e32 v52, 0x3e38aa3b, v54
	v_cmp_lt_i32_e32 vcc, 17, v179
	v_mul_f32_e32 v32, 0x3e38aa3b, v32
	s_nop 0
	v_cndmask_b32_e32 v88, v203, v52, vcc
	v_mul_f32_e32 v52, 0x3e38aa3b, v55
	v_cmp_lt_i32_e32 vcc, 18, v179
	s_nop 1
	v_cndmask_b32_e32 v89, v203, v52, vcc
	v_cmp_lt_i32_e32 vcc, 31, v179
	s_nop 1
	v_cndmask_b32_e32 v90, v203, v40, vcc
	v_mul_f32_e32 v40, 0x3e38aa3b, v41
	v_cmp_lt_i32_e32 vcc, 32, v179
	s_nop 1
	v_cndmask_b32_e32 v91, v203, v40, vcc
	v_mul_f32_e32 v40, 0x3e38aa3b, v42
	v_cmp_lt_i32_e32 vcc, 33, v179
	s_nop 1
	v_cndmask_b32_e32 v104, v203, v40, vcc
	v_mul_f32_e32 v40, 0x3e38aa3b, v43
	v_cmp_lt_i32_e32 vcc, 34, v179
	s_nop 1
	v_cndmask_b32_e32 v105, v203, v40, vcc
	v_cmp_lt_i32_e32 vcc, 47, v179
	s_nop 1
	v_cndmask_b32_e32 v106, v203, v32, vcc
	v_mul_f32_e32 v32, 0x3e38aa3b, v33
	v_cmp_lt_i32_e32 vcc, 48, v179
	s_nop 1
	v_cndmask_b32_e32 v107, v203, v32, vcc
	v_mul_f32_e32 v32, 0x3e38aa3b, v34
	v_cmp_lt_i32_e32 vcc, 49, v179
	s_nop 1
	v_cndmask_b32_e32 v108, v203, v32, vcc
	v_mul_f32_e32 v32, 0x3e38aa3b, v35
	v_cmp_lt_i32_e32 vcc, 50, v179
	s_nop 1
	v_cndmask_b32_e32 v109, v203, v32, vcc
.Lc2_tail:
	v_lshlrev_b64 v[80:81], 7, v[0:1]
	v_lshl_add_u64 v[32:33], v[122:123], 0, v[80:81]
	global_load_dwordx4 v[68:71], v[32:33], off
	global_load_dwordx4 v[64:67], v[32:33], off offset:1024
	global_load_dwordx4 v[60:63], v[32:33], off offset:2048
	global_load_dwordx4 v[52:55], v[32:33], off offset:3072
	v_add_co_u32_e32 v32, vcc, s33, v32
	s_nop 1
	v_addc_co_u32_e32 v33, vcc, 0, v33, vcc
	global_load_dwordx4 v[44:47], v[32:33], off
	global_load_dwordx4 v[40:43], v[32:33], off offset:1024
	global_load_dwordx4 v[36:39], v[32:33], off offset:2048
	s_nop 0
	global_load_dwordx4 v[32:35], v[32:33], off offset:3072
	v_sub_f32_e32 v0, v82, v180
	v_exp_f32_e32 v82, v0
	v_sub_f32_e32 v0, v83, v180
	v_exp_f32_e32 v83, v0
	v_sub_f32_e32 v0, v84, v180
	v_pk_mul_f32 v[184:185], v[2:3], v[82:83]
	v_exp_f32_e32 v82, v0
	v_sub_f32_e32 v0, v85, v180
	v_exp_f32_e32 v83, v0
	v_sub_f32_e32 v0, v86, v180
	v_exp_f32_e32 v84, v0
	v_sub_f32_e32 v0, v87, v180
	v_exp_f32_e32 v85, v0
	v_sub_f32_e32 v0, v88, v180
	v_exp_f32_e32 v86, v0
	v_sub_f32_e32 v0, v89, v180
	v_exp_f32_e32 v87, v0
	v_sub_f32_e32 v0, v90, v180
	v_exp_f32_e32 v88, v0
	v_sub_f32_e32 v0, v91, v180
	v_exp_f32_e32 v89, v0
	v_sub_f32_e32 v0, v104, v180
	v_pk_mul_f32 v[188:189], v[2:3], v[82:83]
	v_exp_f32_e32 v82, v0
	v_sub_f32_e32 v0, v105, v180
	v_exp_f32_e32 v83, v0
	v_sub_f32_e32 v0, v106, v180
	v_pk_mul_f32 v[190:191], v[2:3], v[84:85]
	v_exp_f32_e32 v84, v0
	v_sub_f32_e32 v0, v107, v180
	v_exp_f32_e32 v85, v0
	v_sub_f32_e32 v0, v108, v180
	v_pk_mul_f32 v[194:195], v[2:3], v[86:87]
	v_exp_f32_e32 v86, v0
	v_sub_f32_e32 v0, v109, v180
	v_exp_f32_e32 v87, v0
	v_cvt_pk_bf16_f32 v112, v184, v185
	v_cvt_pk_bf16_f32 v113, v188, v189
	v_cvt_pk_bf16_f32 v114, v190, v191
	v_cvt_pk_bf16_f32 v115, v194, v195
	v_pk_mul_f32 v[198:199], v[2:3], v[88:89]
	v_pk_mul_f32 v[204:205], v[2:3], v[82:83]
	v_mfma_f32_16x16x32_bf16 v[24:27], v[24:27], v[112:115], v[72:75]
	v_mul_f32_e64 v162, v2, v84
	v_mul_f32_e64 v163, v3, v85
	v_pk_mul_f32 v[160:161], v[2:3], v[86:87]
	v_cvt_pk_bf16_f32 v104, v198, v199
	v_mfma_f32_16x16x32_bf16 v[28:31], v[28:31], v[112:115], v[48:51]
	v_cvt_pk_bf16_f32 v105, v204, v205
	v_cvt_pk_bf16_f32 v106, v162, v163
	v_cvt_pk_bf16_f32 v107, v160, v161
	s_nop 1
	v_mfma_f32_16x16x32_bf16 v[72:75], v[12:15], v[104:107], v[24:27]
	v_mfma_f32_16x16x32_bf16 v[48:51], v[20:23], v[104:107], v[28:31]
	v_lshl_add_u64 v[20:21], v[132:133], 0, v[80:81]
	v_add_co_u32_e32 v108, vcc, s33, v20
	global_load_dwordx4 v[24:27], v[20:21], off
	global_load_dwordx4 v[12:15], v[20:21], off offset:1024
	global_load_dwordx4 v[80:83], v[20:21], off offset:2048
	global_load_dwordx4 v[84:87], v[20:21], off offset:3072
	v_addc_co_u32_e32 v109, vcc, 0, v21, vcc
	global_load_dwordx4 v[28:31], v[108:109], off
	global_load_dwordx4 v[20:23], v[108:109], off offset:1024
	global_load_dwordx4 v[88:91], v[108:109], off offset:2048
	s_nop 0
	global_load_dwordx4 v[108:111], v[108:109], off offset:3072
	v_mov_b32_dpp v186, v188 quad_perm:[1,0,3,2] row_mask:0xf bank_mask:0xf
	v_mov_b32_dpp v196, v195 quad_perm:[1,0,3,2] row_mask:0xf bank_mask:0xf
	v_mov_b32_dpp v206, v205 quad_perm:[1,0,3,2] row_mask:0xf bank_mask:0xf
	v_mov_b32_dpp v209, v161 quad_perm:[1,0,3,2] row_mask:0xf bank_mask:0xf
	v_mov_b32_dpp v0, v184 quad_perm:[1,0,3,2] row_mask:0xf bank_mask:0xf
	s_waitcnt lgkmcnt(4)
; #define SB0 __builtin_amdgcn_sched_barrier(0)
; __device__ __forceinline__ void phase_nsa_attn(const Params& p, char* smem, volatile LAS unsigned* vb_) {
;     ...
;           pv64(vA, st, o);
;           SB0;
;           v_load64(vA, Vb + (size_t)nn * 64, lane);
;           SB0;
;           float mainv[4], ev[4], eup[4];
; #pragma unroll
;           for (int kt = 0; kt < 4; ++kt) {
;             float acc = 0.f, last = 0.f;
; #pragma unroll
;             for (int r = 0; r < 4; ++r) {
;               float a = st[kt][r];
;               a += __shfl_xor(a, 1);
;               a += __shfl_xor(a, 2);
;               acc += a;
;               last = a;
;             }
;             mainv[kt] = acc; ev[kt] = last;
;           }
; #pragma unroll
;           for (int kt = 0; kt < 4; ++kt) eup[kt] = __shfl(ev[kt], (lane + 48) & 63);
; #pragma unroll
;           for (int kt = 0; kt < 4; ++kt) {
;             const float pe = (q > 0) ? eup[kt] : (kt > 0 ? eup[kt > 0 ? kt - 1 : 0] : carry);
;             if (g == 0) impl[tq * 128 + (n0 >> 2) + kt * 4 + q] = mainv[kt] + pe;
;           }
;           carry = eup[3];
	v_add_f32_e32 v186, v188, v186
	v_mov_b32_dpp v188, v189 quad_perm:[1,0,3,2] row_mask:0xf bank_mask:0xf
	s_waitcnt lgkmcnt(4)
	v_add_f32_e32 v195, v195, v196
	s_nop 1
	v_mov_b32_dpp v196, v195 quad_perm:[2,3,0,1] row_mask:0xf bank_mask:0xf
	s_waitcnt lgkmcnt(4)
	v_add_f32_e32 v205, v205, v206
	s_nop 1
	v_mov_b32_dpp v206, v205 quad_perm:[2,3,0,1] row_mask:0xf bank_mask:0xf
	s_waitcnt lgkmcnt(2)
	v_add_f32_e32 v188, v189, v188
	s_nop 1
	v_mov_b32_dpp v189, v188 quad_perm:[2,3,0,1] row_mask:0xf bank_mask:0xf
	s_waitcnt lgkmcnt(2)
	v_add_f32_e32 v195, v195, v196
	v_mov_b32_dpp v196, v198 quad_perm:[1,0,3,2] row_mask:0xf bank_mask:0xf
	v_add_f32_e32 v161, v161, v209
	v_add_f32_e32 v0, v184, v0
	v_mov_b32_dpp v184, v185 quad_perm:[1,0,3,2] row_mask:0xf bank_mask:0xf
	s_waitcnt lgkmcnt(2)
	v_add_f32_e32 v188, v188, v189
	v_mov_b32_dpp v189, v190 quad_perm:[1,0,3,2] row_mask:0xf bank_mask:0xf
	v_mov_b32_dpp v192, v191 quad_perm:[1,0,3,2] row_mask:0xf bank_mask:0xf
	v_mov_b32_dpp v193, v194 quad_perm:[1,0,3,2] row_mask:0xf bank_mask:0xf
	s_waitcnt lgkmcnt(4)
	v_add_f32_e32 v196, v198, v196
	v_mov_b32_dpp v198, v199 quad_perm:[1,0,3,2] row_mask:0xf bank_mask:0xf
	v_mov_b32_dpp v200, v204 quad_perm:[1,0,3,2] row_mask:0xf bank_mask:0xf
	v_add_f32_e32 v205, v205, v206
	v_mov_b32_dpp v206, v162 quad_perm:[1,0,3,2] row_mask:0xf bank_mask:0xf
	v_mov_b32_dpp v207, v163 quad_perm:[1,0,3,2] row_mask:0xf bank_mask:0xf
	v_mov_b32_dpp v208, v160 quad_perm:[1,0,3,2] row_mask:0xf bank_mask:0xf
	v_mov_b32_dpp v209, v161 quad_perm:[2,3,0,1] row_mask:0xf bank_mask:0xf
	v_mfma_f32_16x16x32_bf16 v[56:59], v[100:103], v[112:115], v[56:59]
	s_waitcnt lgkmcnt(9)
	v_add_f32_e32 v184, v185, v184
	s_waitcnt lgkmcnt(8)
	v_add_f32_e32 v189, v190, v189
	s_waitcnt lgkmcnt(7)
	v_add_f32_e32 v191, v191, v192
	s_waitcnt lgkmcnt(6)
	v_add_f32_e32 v193, v194, v193
	s_waitcnt lgkmcnt(5)
	v_add_f32_e32 v198, v199, v198
	s_waitcnt lgkmcnt(4)
	v_add_f32_e32 v200, v204, v200
	s_waitcnt lgkmcnt(3)
	v_add_f32_e32 v162, v162, v206
	s_waitcnt lgkmcnt(2)
	v_add_f32_e32 v163, v163, v207
	s_waitcnt lgkmcnt(1)
	v_add_f32_e32 v160, v160, v208
	s_waitcnt lgkmcnt(0)
	v_add_f32_e32 v161, v161, v209
	v_mov_b32_dpp v183, v0 quad_perm:[2,3,0,1] row_mask:0xf bank_mask:0xf
	v_mov_b32_dpp v185, v184 quad_perm:[2,3,0,1] row_mask:0xf bank_mask:0xf
	v_mov_b32_dpp v187, v186 quad_perm:[2,3,0,1] row_mask:0xf bank_mask:0xf
	v_mov_b32_dpp v190, v189 quad_perm:[2,3,0,1] row_mask:0xf bank_mask:0xf
	v_mov_b32_dpp v192, v191 quad_perm:[2,3,0,1] row_mask:0xf bank_mask:0xf
	v_mov_b32_dpp v194, v193 quad_perm:[2,3,0,1] row_mask:0xf bank_mask:0xf
	v_mov_b32_dpp v197, v196 quad_perm:[2,3,0,1] row_mask:0xf bank_mask:0xf
	v_mov_b32_dpp v199, v198 quad_perm:[2,3,0,1] row_mask:0xf bank_mask:0xf
	v_mov_b32_dpp v204, v200 quad_perm:[2,3,0,1] row_mask:0xf bank_mask:0xf
	v_mov_b32_dpp v206, v162 quad_perm:[2,3,0,1] row_mask:0xf bank_mask:0xf
	v_mov_b32_dpp v207, v163 quad_perm:[2,3,0,1] row_mask:0xf bank_mask:0xf
	v_mov_b32_dpp v208, v160 quad_perm:[2,3,0,1] row_mask:0xf bank_mask:0xf
	v_mfma_f32_16x16x32_bf16 v[56:59], v[92:95], v[104:107], v[56:59]
	ds_bpermute_b32 v95, v172, v188
	ds_bpermute_b32 v94, v172, v195
	ds_bpermute_b32 v93, v172, v205
	ds_bpermute_b32 v92, v172, v161
	v_mfma_f32_16x16x32_bf16 v[76:79], v[96:99], v[112:115], v[76:79]
	s_and_saveexec_b64 s[20:21], s[44:45]
	s_cbranch_execz .LBB0_96
	s_waitcnt lgkmcnt(6)
	v_add_f32_e32 v96, v162, v206
	v_add_f32_e32 v99, v189, v190
	v_add_f32_e32 v96, 0, v96
	s_waitcnt lgkmcnt(5)
	v_add_f32_e32 v97, v163, v207
	v_add_f32_e32 v99, 0, v99
	v_add_f32_e32 v100, v191, v192
	v_add_f32_e32 v96, v96, v97
	s_waitcnt lgkmcnt(4)
	v_add_f32_e32 v97, v160, v208
	v_add_f32_e32 v99, v99, v100
	v_add_f32_e32 v100, v193, v194
	v_add_f32_e32 v0, v0, v183
	v_add_f32_e32 v96, v96, v97
	v_add_f32_e32 v97, v196, v197
	v_add_f32_e32 v99, v99, v100
	v_add_f32_e32 v0, 0, v0
	v_add_f32_e32 v100, v184, v185
	v_add_f32_e32 v97, 0, v97
	v_add_f32_e32 v98, v198, v199
	v_add_f32_e32 v0, v0, v100
	v_add_f32_e32 v100, v186, v187
	v_add_f32_e32 v97, v97, v98
	v_add_f32_e32 v98, v200, v204
	v_add_f32_e32 v0, v0, v100
	v_add_f32_e32 v97, v97, v98
	s_waitcnt lgkmcnt(3)
	v_cndmask_b32_e64 v98, v95, v181, s[42:43]
	v_add_f32_e32 v99, v99, v195
	v_add_f32_e32 v0, v0, v188
	s_waitcnt lgkmcnt(2)
	v_cndmask_b32_e64 v95, v94, v95, s[42:43]
	v_add_f32_e32 v0, v0, v98
	v_add_f32_e32 v95, v99, v95
	v_add_f32_e32 v96, v96, v161
	v_add_f32_e32 v97, v97, v205
	ds_write2_b32 v182, v0, v95 offset1:4
	s_waitcnt lgkmcnt(2)
	v_cndmask_b32_e64 v0, v93, v94, s[42:43]
	s_waitcnt lgkmcnt(1)
	v_cndmask_b32_e64 v93, v92, v93, s[42:43]
	v_add_f32_e32 v0, v97, v0
	v_add_f32_e32 v93, v96, v93
	ds_write2_b32 v182, v0, v93 offset0:8 offset1:12
	s_branch .LBB0_96
